# peeled first iteration (no accumulator zero-init) plus dead row-index instructions removed from the FFN-in epilogue
# baseline (speedup 1.0000x reference)
.LBB0_495:
	s_waitcnt lgkmcnt(0)
	v_mul_f32_e32 v146, 0xbfb8aa3b, v144
	v_pk_mul_f32 v[148:149], v[126:127], v[146:147] op_sel_hi:[1,0]
	v_mul_f32_e32 v144, v144, v144
	v_exp_f32_e32 v148, v148
	v_exp_f32_e32 v149, v149
	v_pk_mul_f32 v[122:123], v[126:127], v[122:123]
	v_pk_mul_f32 v[124:125], v[128:129], v[124:125]
	v_pk_mul_f32 v[120:121], v[116:117], v[120:121]
	v_pk_add_f32 v[148:149], v[148:149], 1.0 op_sel_hi:[1,0]
	v_lshl_or_b32 v134, s90, 7, v141
	v_rcp_f32_e32 v148, v148
	v_rcp_f32_e32 v149, v149
	v_ashrrev_i32_e32 v135, 31, v134
	s_mov_b64 s[68:69], -1
	s_and_b64 vcc, exec, s[52:53]
	v_pk_mul_f32 v[126:127], v[144:145], v[148:149] op_sel_hi:[0,1]
	v_pk_mul_f32 v[122:123], v[122:123], v[126:127]
	v_pk_mul_f32 v[126:127], v[128:129], v[146:147] op_sel_hi:[1,0]
	s_nop 0
	v_exp_f32_e32 v126, v126
	v_exp_f32_e32 v127, v127
	s_nop 0
	v_pk_add_f32 v[126:127], v[126:127], 1.0 op_sel_hi:[1,0]
	s_nop 0
	v_rcp_f32_e32 v126, v126
	v_rcp_f32_e32 v127, v127
	s_nop 0
	v_pk_mul_f32 v[126:127], v[144:145], v[126:127] op_sel_hi:[0,1]
	v_pk_mul_f32 v[124:125], v[124:125], v[126:127]
	v_pk_mul_f32 v[126:127], v[114:115], v[146:147] op_sel_hi:[1,0]
	v_pk_mul_f32 v[114:115], v[114:115], v[118:119]
	v_exp_f32_e32 v126, v126
	v_exp_f32_e32 v127, v127
	s_nop 0
	v_pk_add_f32 v[126:127], v[126:127], 1.0 op_sel_hi:[1,0]
	s_nop 0
	v_rcp_f32_e32 v126, v126
	v_rcp_f32_e32 v127, v127
	s_nop 0
	v_pk_mul_f32 v[118:119], v[144:145], v[126:127] op_sel_hi:[0,1]
	v_pk_mul_f32 v[118:119], v[114:115], v[118:119]
	v_pk_mul_f32 v[114:115], v[116:117], v[146:147] op_sel_hi:[1,0]
	s_nop 0
	v_exp_f32_e32 v114, v114
	v_exp_f32_e32 v115, v115
	s_nop 0
	v_pk_add_f32 v[114:115], v[114:115], 1.0 op_sel_hi:[1,0]
	s_nop 0
	v_rcp_f32_e32 v114, v114
	v_rcp_f32_e32 v115, v115
	s_nop 0
	v_pk_mul_f32 v[114:115], v[144:145], v[114:115] op_sel_hi:[0,1]
	v_pk_mul_f32 v[120:121], v[120:121], v[114:115]
	v_cvt_pk_bf16_f32 v114, v122, v123
	v_cvt_pk_bf16_f32 v115, v124, v125
	v_cvt_pk_bf16_f32 v116, v118, v119
	v_mov_b64_e32 v[118:119], s[40:41]
	v_mad_u64_u32 v[118:119], s[20:21], v136, s17, v[118:119]
	v_cvt_pk_bf16_f32 v117, v120, v121
	v_mov_b32_e32 v120, v119
	v_mad_u64_u32 v[120:121], s[20:21], v137, s17, v[120:121]
	v_mov_b32_e32 v119, v120
	v_lshl_add_u64 v[150:151], v[134:135], 1, v[118:119]
	global_store_dwordx4 v[150:151], v[114:117], off sc1
	s_nop 1
	s_cbranch_vccnz .LBB0_497
	ds_read_b32 v116, v143 offset:64
	s_mov_b64 s[68:69], 0

.LBB0_499:
	s_waitcnt lgkmcnt(0)
	v_mul_f32_e32 v118, 0xbfb8aa3b, v116
	v_pk_mul_f32 v[120:121], v[110:111], v[118:119] op_sel_hi:[1,0]
	v_mul_f32_e32 v116, v116, v116
	v_exp_f32_e32 v120, v120
	v_exp_f32_e32 v121, v121
	v_pk_mul_f32 v[106:107], v[110:111], v[106:107]
	v_pk_mul_f32 v[108:109], v[112:113], v[108:109]
	v_pk_mul_f32 v[104:105], v[100:101], v[104:105]
	v_pk_add_f32 v[120:121], v[120:121], 1.0 op_sel_hi:[1,0]
	s_mov_b64 s[68:69], -1
	v_rcp_f32_e32 v120, v120
	v_rcp_f32_e32 v121, v121
	s_and_b64 vcc, exec, s[52:53]
	v_pk_mul_f32 v[110:111], v[116:117], v[120:121] op_sel_hi:[0,1]
	v_pk_mul_f32 v[106:107], v[106:107], v[110:111]
	v_pk_mul_f32 v[110:111], v[112:113], v[118:119] op_sel_hi:[1,0]
	s_nop 0
	v_exp_f32_e32 v110, v110
	v_exp_f32_e32 v111, v111
	s_nop 0
	v_pk_add_f32 v[110:111], v[110:111], 1.0 op_sel_hi:[1,0]
	s_nop 0
	v_rcp_f32_e32 v110, v110
	v_rcp_f32_e32 v111, v111
	s_nop 0
	v_pk_mul_f32 v[110:111], v[116:117], v[110:111] op_sel_hi:[0,1]
	v_pk_mul_f32 v[108:109], v[108:109], v[110:111]
	v_pk_mul_f32 v[110:111], v[98:99], v[118:119] op_sel_hi:[1,0]
	v_pk_mul_f32 v[98:99], v[98:99], v[102:103]
	v_exp_f32_e32 v110, v110
	v_exp_f32_e32 v111, v111
	s_nop 0
	v_pk_add_f32 v[110:111], v[110:111], 1.0 op_sel_hi:[1,0]
	s_nop 0
	v_rcp_f32_e32 v110, v110
	v_rcp_f32_e32 v111, v111
	s_nop 0
	v_pk_mul_f32 v[102:103], v[116:117], v[110:111] op_sel_hi:[0,1]
	v_pk_mul_f32 v[102:103], v[98:99], v[102:103]
	v_pk_mul_f32 v[98:99], v[100:101], v[118:119] op_sel_hi:[1,0]
	s_nop 0
	v_exp_f32_e32 v98, v98
	v_exp_f32_e32 v99, v99
	s_nop 0
	v_pk_add_f32 v[98:99], v[98:99], 1.0 op_sel_hi:[1,0]
	s_nop 0
	v_rcp_f32_e32 v98, v98
	v_rcp_f32_e32 v99, v99
	s_nop 0
	v_pk_mul_f32 v[98:99], v[116:117], v[98:99] op_sel_hi:[0,1]
	v_pk_mul_f32 v[104:105], v[104:105], v[98:99]
	v_cvt_pk_bf16_f32 v98, v106, v107
	v_cvt_pk_bf16_f32 v99, v108, v109
	v_cvt_pk_bf16_f32 v100, v102, v103
	v_cvt_pk_bf16_f32 v101, v104, v105
	s_mul_i32 s20, s17, 0x10
	s_mov_b32 s21, 0
	v_lshl_add_u64 v[102:103], s[20:21], 0, v[150:151]
	global_store_dwordx4 v[102:103], v[98:101], off sc1
	s_nop 1
	s_cbranch_vccnz .LBB0_501
	ds_read_b32 v100, v143 offset:128
	s_mov_b64 s[68:69], 0

.LBB0_503:
	s_waitcnt lgkmcnt(0)
	v_mul_f32_e32 v102, 0xbfb8aa3b, v100
	v_pk_mul_f32 v[104:105], v[94:95], v[102:103] op_sel_hi:[1,0]
	v_mul_f32_e32 v100, v100, v100
	v_exp_f32_e32 v104, v104
	v_exp_f32_e32 v105, v105
	v_pk_mul_f32 v[90:91], v[94:95], v[90:91]
	v_pk_mul_f32 v[92:93], v[96:97], v[92:93]
	v_pk_mul_f32 v[88:89], v[84:85], v[88:89]
	v_pk_add_f32 v[104:105], v[104:105], 1.0 op_sel_hi:[1,0]
	s_mov_b64 s[68:69], -1
	v_rcp_f32_e32 v104, v104
	v_rcp_f32_e32 v105, v105
	s_and_b64 vcc, exec, s[52:53]
	v_pk_mul_f32 v[94:95], v[100:101], v[104:105] op_sel_hi:[0,1]
	v_pk_mul_f32 v[90:91], v[90:91], v[94:95]
	v_pk_mul_f32 v[94:95], v[96:97], v[102:103] op_sel_hi:[1,0]
	s_nop 0
	v_exp_f32_e32 v94, v94
	v_exp_f32_e32 v95, v95
	s_nop 0
	v_pk_add_f32 v[94:95], v[94:95], 1.0 op_sel_hi:[1,0]
	s_nop 0
	v_rcp_f32_e32 v94, v94
	v_rcp_f32_e32 v95, v95
	s_nop 0
	v_pk_mul_f32 v[94:95], v[100:101], v[94:95] op_sel_hi:[0,1]
	v_pk_mul_f32 v[92:93], v[92:93], v[94:95]
	v_pk_mul_f32 v[94:95], v[82:83], v[102:103] op_sel_hi:[1,0]
	v_pk_mul_f32 v[82:83], v[82:83], v[86:87]
	v_exp_f32_e32 v94, v94
	v_exp_f32_e32 v95, v95
	s_nop 0
	v_pk_add_f32 v[94:95], v[94:95], 1.0 op_sel_hi:[1,0]
	s_nop 0
	v_rcp_f32_e32 v94, v94
	v_rcp_f32_e32 v95, v95
	s_nop 0
	v_pk_mul_f32 v[86:87], v[100:101], v[94:95] op_sel_hi:[0,1]
	v_pk_mul_f32 v[86:87], v[82:83], v[86:87]
	v_pk_mul_f32 v[82:83], v[84:85], v[102:103] op_sel_hi:[1,0]
	s_nop 0
	v_exp_f32_e32 v82, v82
	v_exp_f32_e32 v83, v83
	s_nop 0
	v_pk_add_f32 v[82:83], v[82:83], 1.0 op_sel_hi:[1,0]
	s_nop 0
	v_rcp_f32_e32 v82, v82
	v_rcp_f32_e32 v83, v83
	s_nop 0
	v_pk_mul_f32 v[82:83], v[100:101], v[82:83] op_sel_hi:[0,1]
	v_pk_mul_f32 v[88:89], v[88:89], v[82:83]
	v_cvt_pk_bf16_f32 v82, v90, v91
	v_cvt_pk_bf16_f32 v83, v92, v93
	v_cvt_pk_bf16_f32 v84, v86, v87
	v_cvt_pk_bf16_f32 v85, v88, v89
	s_mul_i32 s20, s17, 0x20
	s_mov_b32 s21, 0
	v_lshl_add_u64 v[86:87], s[20:21], 0, v[150:151]
	global_store_dwordx4 v[86:87], v[82:85], off sc1
	s_nop 1
	s_cbranch_vccnz .LBB0_505
	ds_read_b32 v84, v143 offset:192
	s_mov_b64 s[68:69], 0

.LBB0_507:
	s_waitcnt lgkmcnt(0)
	v_mul_f32_e32 v86, 0xbfb8aa3b, v84
	v_pk_mul_f32 v[88:89], v[78:79], v[86:87] op_sel_hi:[1,0]
	v_mul_f32_e32 v84, v84, v84
	v_exp_f32_e32 v88, v88
	v_exp_f32_e32 v89, v89
	v_pk_mul_f32 v[74:75], v[78:79], v[74:75]
	v_pk_mul_f32 v[76:77], v[80:81], v[76:77]
	v_pk_mul_f32 v[72:73], v[68:69], v[72:73]
	v_pk_add_f32 v[88:89], v[88:89], 1.0 op_sel_hi:[1,0]
	s_mov_b64 s[68:69], -1
	v_rcp_f32_e32 v88, v88
	v_rcp_f32_e32 v89, v89
	s_and_b64 vcc, exec, s[52:53]
	v_pk_mul_f32 v[78:79], v[84:85], v[88:89] op_sel_hi:[0,1]
	v_pk_mul_f32 v[74:75], v[74:75], v[78:79]
	v_pk_mul_f32 v[78:79], v[80:81], v[86:87] op_sel_hi:[1,0]
	s_nop 0
	v_exp_f32_e32 v78, v78
	v_exp_f32_e32 v79, v79
	s_nop 0
	v_pk_add_f32 v[78:79], v[78:79], 1.0 op_sel_hi:[1,0]
	s_nop 0
	v_rcp_f32_e32 v78, v78
	v_rcp_f32_e32 v79, v79
	s_nop 0
	v_pk_mul_f32 v[78:79], v[84:85], v[78:79] op_sel_hi:[0,1]
	v_pk_mul_f32 v[76:77], v[76:77], v[78:79]
	v_pk_mul_f32 v[78:79], v[66:67], v[86:87] op_sel_hi:[1,0]
	v_pk_mul_f32 v[66:67], v[66:67], v[70:71]
	v_exp_f32_e32 v78, v78
	v_exp_f32_e32 v79, v79
	s_nop 0
	v_pk_add_f32 v[78:79], v[78:79], 1.0 op_sel_hi:[1,0]
	s_nop 0
	v_rcp_f32_e32 v78, v78
	v_rcp_f32_e32 v79, v79
	s_nop 0
	v_pk_mul_f32 v[70:71], v[84:85], v[78:79] op_sel_hi:[0,1]
	v_pk_mul_f32 v[70:71], v[66:67], v[70:71]
	v_pk_mul_f32 v[66:67], v[68:69], v[86:87] op_sel_hi:[1,0]
	s_nop 0
	v_exp_f32_e32 v66, v66
	v_exp_f32_e32 v67, v67
	s_nop 0
	v_pk_add_f32 v[66:67], v[66:67], 1.0 op_sel_hi:[1,0]
	s_nop 0
	v_rcp_f32_e32 v66, v66
	v_rcp_f32_e32 v67, v67
	s_nop 0
	v_pk_mul_f32 v[66:67], v[84:85], v[66:67] op_sel_hi:[0,1]
	v_pk_mul_f32 v[72:73], v[72:73], v[66:67]
	v_cvt_pk_bf16_f32 v66, v74, v75
	v_cvt_pk_bf16_f32 v67, v76, v77
	v_cvt_pk_bf16_f32 v68, v70, v71
	v_cvt_pk_bf16_f32 v69, v72, v73
	s_mul_i32 s20, s17, 0x30
	s_mov_b32 s21, 0
	v_lshl_add_u64 v[70:71], s[20:21], 0, v[150:151]
	global_store_dwordx4 v[70:71], v[66:69], off sc1
	s_nop 1
	s_cbranch_vccnz .LBB0_509
	ds_read_b32 v68, v143 offset:512
	s_mov_b64 s[68:69], 0

.LBB0_511:
	s_waitcnt lgkmcnt(0)
	v_mul_f32_e32 v70, 0xbfb8aa3b, v68
	v_pk_mul_f32 v[72:73], v[62:63], v[70:71] op_sel_hi:[1,0]
	v_mul_f32_e32 v68, v68, v68
	v_exp_f32_e32 v72, v72
	v_exp_f32_e32 v73, v73
	v_pk_mul_f32 v[58:59], v[62:63], v[58:59]
	v_pk_mul_f32 v[60:61], v[64:65], v[60:61]
	v_pk_mul_f32 v[56:57], v[52:53], v[56:57]
	v_pk_add_f32 v[72:73], v[72:73], 1.0 op_sel_hi:[1,0]
	s_mov_b64 s[68:69], -1
	v_rcp_f32_e32 v72, v72
	v_rcp_f32_e32 v73, v73
	s_and_b64 vcc, exec, s[52:53]
	v_pk_mul_f32 v[62:63], v[68:69], v[72:73] op_sel_hi:[0,1]
	v_pk_mul_f32 v[58:59], v[58:59], v[62:63]
	v_pk_mul_f32 v[62:63], v[64:65], v[70:71] op_sel_hi:[1,0]
	s_nop 0
	v_exp_f32_e32 v62, v62
	v_exp_f32_e32 v63, v63
	s_nop 0
	v_pk_add_f32 v[62:63], v[62:63], 1.0 op_sel_hi:[1,0]
	s_nop 0
	v_rcp_f32_e32 v62, v62
	v_rcp_f32_e32 v63, v63
	s_nop 0
	v_pk_mul_f32 v[62:63], v[68:69], v[62:63] op_sel_hi:[0,1]
	v_pk_mul_f32 v[60:61], v[60:61], v[62:63]
	v_pk_mul_f32 v[62:63], v[50:51], v[70:71] op_sel_hi:[1,0]
	v_pk_mul_f32 v[50:51], v[50:51], v[54:55]
	v_exp_f32_e32 v62, v62
	v_exp_f32_e32 v63, v63
	s_nop 0
	v_pk_add_f32 v[62:63], v[62:63], 1.0 op_sel_hi:[1,0]
	s_nop 0
	v_rcp_f32_e32 v62, v62
	v_rcp_f32_e32 v63, v63
	s_nop 0
	v_pk_mul_f32 v[54:55], v[68:69], v[62:63] op_sel_hi:[0,1]
	v_pk_mul_f32 v[54:55], v[50:51], v[54:55]
	v_pk_mul_f32 v[50:51], v[52:53], v[70:71] op_sel_hi:[1,0]
	s_nop 0
	v_exp_f32_e32 v50, v50
	v_exp_f32_e32 v51, v51
	s_nop 0
	v_pk_add_f32 v[50:51], v[50:51], 1.0 op_sel_hi:[1,0]
	s_nop 0
	v_rcp_f32_e32 v50, v50
	v_rcp_f32_e32 v51, v51
	s_nop 0
	v_pk_mul_f32 v[50:51], v[68:69], v[50:51] op_sel_hi:[0,1]
	v_pk_mul_f32 v[56:57], v[56:57], v[50:51]
	v_cvt_pk_bf16_f32 v50, v58, v59
	v_cvt_pk_bf16_f32 v51, v60, v61
	v_cvt_pk_bf16_f32 v52, v54, v55
	v_cvt_pk_bf16_f32 v53, v56, v57
	s_mul_i32 s20, s17, 0x80
	s_mov_b32 s21, 0
	v_lshl_add_u64 v[54:55], s[20:21], 0, v[150:151]
	global_store_dwordx4 v[54:55], v[50:53], off sc1
	s_nop 1
	s_cbranch_vccnz .LBB0_513
	ds_read_b32 v52, v143 offset:576
	s_mov_b64 s[68:69], 0

.LBB0_515:
	s_waitcnt lgkmcnt(0)
	v_mul_f32_e32 v54, 0xbfb8aa3b, v52
	v_pk_mul_f32 v[56:57], v[46:47], v[54:55] op_sel_hi:[1,0]
	v_mul_f32_e32 v52, v52, v52
	v_exp_f32_e32 v56, v56
	v_exp_f32_e32 v57, v57
	v_pk_mul_f32 v[42:43], v[46:47], v[42:43]
	v_pk_mul_f32 v[44:45], v[48:49], v[44:45]
	v_pk_mul_f32 v[40:41], v[36:37], v[40:41]
	v_pk_add_f32 v[56:57], v[56:57], 1.0 op_sel_hi:[1,0]
	s_mov_b64 s[68:69], -1
	v_rcp_f32_e32 v56, v56
	v_rcp_f32_e32 v57, v57
	s_and_b64 vcc, exec, s[52:53]
	v_pk_mul_f32 v[46:47], v[52:53], v[56:57] op_sel_hi:[0,1]
	v_pk_mul_f32 v[42:43], v[42:43], v[46:47]
	v_pk_mul_f32 v[46:47], v[48:49], v[54:55] op_sel_hi:[1,0]
	s_nop 0
	v_exp_f32_e32 v46, v46
	v_exp_f32_e32 v47, v47
	s_nop 0
	v_pk_add_f32 v[46:47], v[46:47], 1.0 op_sel_hi:[1,0]
	s_nop 0
	v_rcp_f32_e32 v46, v46
	v_rcp_f32_e32 v47, v47
	s_nop 0
	v_pk_mul_f32 v[46:47], v[52:53], v[46:47] op_sel_hi:[0,1]
	v_pk_mul_f32 v[44:45], v[44:45], v[46:47]
	v_pk_mul_f32 v[46:47], v[34:35], v[54:55] op_sel_hi:[1,0]
	v_pk_mul_f32 v[34:35], v[34:35], v[38:39]
	v_exp_f32_e32 v46, v46
	v_exp_f32_e32 v47, v47
	s_nop 0
	v_pk_add_f32 v[46:47], v[46:47], 1.0 op_sel_hi:[1,0]
	s_nop 0
	v_rcp_f32_e32 v46, v46
	v_rcp_f32_e32 v47, v47
	s_nop 0
	v_pk_mul_f32 v[38:39], v[52:53], v[46:47] op_sel_hi:[0,1]
	v_pk_mul_f32 v[38:39], v[34:35], v[38:39]
	v_pk_mul_f32 v[34:35], v[36:37], v[54:55] op_sel_hi:[1,0]
	s_nop 0
	v_exp_f32_e32 v34, v34
	v_exp_f32_e32 v35, v35
	s_nop 0
	v_pk_add_f32 v[34:35], v[34:35], 1.0 op_sel_hi:[1,0]
	s_nop 0
	v_rcp_f32_e32 v34, v34
	v_rcp_f32_e32 v35, v35
	s_nop 0
	v_pk_mul_f32 v[34:35], v[52:53], v[34:35] op_sel_hi:[0,1]
	v_pk_mul_f32 v[40:41], v[40:41], v[34:35]
	v_cvt_pk_bf16_f32 v34, v42, v43
	v_cvt_pk_bf16_f32 v35, v44, v45
	v_cvt_pk_bf16_f32 v36, v38, v39
	v_cvt_pk_bf16_f32 v37, v40, v41
	s_mul_i32 s20, s17, 0x90
	s_mov_b32 s21, 0
	v_lshl_add_u64 v[38:39], s[20:21], 0, v[150:151]
	global_store_dwordx4 v[38:39], v[34:37], off sc1
	s_nop 1
	s_cbranch_vccnz .LBB0_517
	ds_read_b32 v36, v143 offset:640
	s_mov_b64 s[68:69], 0

.LBB0_519:
	s_waitcnt lgkmcnt(0)
	v_mul_f32_e32 v38, 0xbfb8aa3b, v36
	v_pk_mul_f32 v[40:41], v[30:31], v[38:39] op_sel_hi:[1,0]
	v_mul_f32_e32 v36, v36, v36
	v_exp_f32_e32 v40, v40
	v_exp_f32_e32 v41, v41
	v_pk_mul_f32 v[26:27], v[30:31], v[26:27]
	v_pk_mul_f32 v[28:29], v[32:33], v[28:29]
	v_pk_mul_f32 v[24:25], v[20:21], v[24:25]
	v_pk_add_f32 v[40:41], v[40:41], 1.0 op_sel_hi:[1,0]
	s_mov_b64 s[68:69], -1
	v_rcp_f32_e32 v40, v40
	v_rcp_f32_e32 v41, v41
	s_and_b64 vcc, exec, s[52:53]
	v_pk_mul_f32 v[30:31], v[36:37], v[40:41] op_sel_hi:[0,1]
	v_pk_mul_f32 v[26:27], v[26:27], v[30:31]
	v_pk_mul_f32 v[30:31], v[32:33], v[38:39] op_sel_hi:[1,0]
	s_nop 0
	v_exp_f32_e32 v30, v30
	v_exp_f32_e32 v31, v31
	s_nop 0
	v_pk_add_f32 v[30:31], v[30:31], 1.0 op_sel_hi:[1,0]
	s_nop 0
	v_rcp_f32_e32 v30, v30
	v_rcp_f32_e32 v31, v31
	s_nop 0
	v_pk_mul_f32 v[30:31], v[36:37], v[30:31] op_sel_hi:[0,1]
	v_pk_mul_f32 v[28:29], v[28:29], v[30:31]
	v_pk_mul_f32 v[30:31], v[18:19], v[38:39] op_sel_hi:[1,0]
	v_pk_mul_f32 v[18:19], v[18:19], v[22:23]
	v_exp_f32_e32 v30, v30
	v_exp_f32_e32 v31, v31
	s_nop 0
	v_pk_add_f32 v[30:31], v[30:31], 1.0 op_sel_hi:[1,0]
	s_nop 0
	v_rcp_f32_e32 v30, v30
	v_rcp_f32_e32 v31, v31
	s_nop 0
	v_pk_mul_f32 v[22:23], v[36:37], v[30:31] op_sel_hi:[0,1]
	v_pk_mul_f32 v[22:23], v[18:19], v[22:23]
	v_pk_mul_f32 v[18:19], v[20:21], v[38:39] op_sel_hi:[1,0]
	s_nop 0
	v_exp_f32_e32 v18, v18
	v_exp_f32_e32 v19, v19
	s_nop 0
	v_pk_add_f32 v[18:19], v[18:19], 1.0 op_sel_hi:[1,0]
	s_nop 0
	v_rcp_f32_e32 v18, v18
	v_rcp_f32_e32 v19, v19
	s_nop 0
	v_pk_mul_f32 v[18:19], v[36:37], v[18:19] op_sel_hi:[0,1]
	v_pk_mul_f32 v[24:25], v[24:25], v[18:19]
	v_cvt_pk_bf16_f32 v18, v26, v27
	v_cvt_pk_bf16_f32 v19, v28, v29
	v_cvt_pk_bf16_f32 v20, v22, v23
	v_cvt_pk_bf16_f32 v21, v24, v25
	s_mul_i32 s20, s17, 0xa0
	s_mov_b32 s21, 0
	v_lshl_add_u64 v[22:23], s[20:21], 0, v[150:151]
	global_store_dwordx4 v[22:23], v[18:21], off sc1
	s_nop 1
	s_cbranch_vccnz .LBB0_521
	ds_read_b32 v20, v143 offset:704
	s_mov_b64 s[68:69], 0
